# sg_stats next-row prefetch re-added with a store-aware steady-state wait (vmcnt(1): the lane-0 stats store is younger than the prefetched loads); on top of the store-aware norm/hgC waits
# baseline (speedup 1.0000x reference)
; DI void unpack8(const u32x4 w, float (&f)[8]) { f[0] = bflo(w.x); f[1] = bfhi(w.x); f[2] = bflo(w.y); f[3] = bfhi(w.y); f[4] = bflo(w.z); f[5] = bfhi(w.z); f[6] = bflo(w.w); f[7] = bfhi(w.w); }
; DI void sg_stats(const bf16_t* Z, float* stats, int gw, int ngw, int lane) {
;     for (int m = gw; m < T_TOK; m += ngw) {
;         const u32x4* zr = (const u32x4*)(Z + (size_t)m * 4096 + 2048) + lane;
;         float f[4][8]; float s = 0.f;
; #pragma unroll
;         for (int j = 0; j < 4; ++j) { unpack8(zr[64 * j], f[j]);
; #pragma unroll
;             for (int e = 0; e < 8; ++e) s += f[j][e]; }
;         const float mean = wave_sum(s) * (1.f / 2048.f); float q = 0.f;
; #pragma unroll
;         for (int j = 0; j < 4; ++j)
; #pragma unroll
;             for (int e = 0; e < 8; ++e) { const float dd = f[j][e] - mean; q += dd * dd; }
;         const float rstd = rsqrtf(wave_sum(q) * (1.f / 2048.f) + EPS);
;         if (lane == 0) { stats[2 * m] = mean; stats[2 * m + 1] = rstd; }
;     }
.LBB0_1089:
	s_waitcnt lgkmcnt(0)
	s_waitcnt vmcnt(1)
	s_branch .Lsgs_body
.Lsgs_first:
	s_waitcnt lgkmcnt(0)
	s_waitcnt vmcnt(0)
.Lsgs_body:
	v_mov_b32_e32 v10, v44
	v_mov_b32_e32 v11, v45
	v_mov_b32_e32 v12, v46
	v_mov_b32_e32 v13, v47
	v_mov_b32_e32 v14, v48
	v_mov_b32_e32 v15, v49
	v_mov_b32_e32 v16, v50
	v_mov_b32_e32 v17, v51
	v_mov_b32_e32 v18, v52
	v_mov_b32_e32 v19, v53
	v_mov_b32_e32 v20, v54
	v_mov_b32_e32 v21, v55
	v_mov_b32_e32 v22, v56
	v_mov_b32_e32 v23, v57
	v_mov_b32_e32 v24, v58
	v_mov_b32_e32 v25, v59
	v_lshl_add_u64 v[60:61], v[2:3], 0, s[12:13]
	global_load_dwordx4 v[44:47], v[60:61], off
	global_load_dwordx4 v[48:51], v[60:61], off offset:1024
	global_load_dwordx4 v[52:55], v[60:61], off offset:2048
	global_load_dwordx4 v[56:59], v[60:61], off offset:3072
	v_lshlrev_b32_e32 v26, 16, v10
	v_and_b32_e32 v27, 0xffff0000, v10
	v_add_f32_e32 v10, 0, v26
	v_lshlrev_b32_e32 v28, 16, v11
	v_add_f32_e32 v10, v10, v27
	v_and_b32_e32 v11, 0xffff0000, v11
	v_add_f32_e32 v10, v10, v28
	v_lshlrev_b32_e32 v29, 16, v12
	v_add_f32_e32 v10, v10, v11
	v_and_b32_e32 v12, 0xffff0000, v12
	v_add_f32_e32 v10, v10, v29
	v_lshlrev_b32_e32 v30, 16, v13
	v_add_f32_e32 v10, v10, v12
	v_and_b32_e32 v13, 0xffff0000, v13
	v_add_f32_e32 v10, v10, v30
	v_lshlrev_b32_e32 v31, 16, v14
	v_add_f32_e32 v10, v10, v13
	v_and_b32_e32 v14, 0xffff0000, v14
	v_add_f32_e32 v10, v10, v31
	v_lshlrev_b32_e32 v32, 16, v15
	v_add_f32_e32 v10, v10, v14
	v_and_b32_e32 v15, 0xffff0000, v15
	v_add_f32_e32 v10, v10, v32
	v_lshlrev_b32_e32 v33, 16, v16
	v_add_f32_e32 v10, v10, v15
	v_and_b32_e32 v16, 0xffff0000, v16
	v_add_f32_e32 v10, v10, v33
	v_lshlrev_b32_e32 v34, 16, v17
	v_add_f32_e32 v10, v10, v16
	v_and_b32_e32 v17, 0xffff0000, v17
	v_add_f32_e32 v10, v10, v34
	v_lshlrev_b32_e32 v35, 16, v18
	v_add_f32_e32 v10, v10, v17
	v_and_b32_e32 v18, 0xffff0000, v18
	v_add_f32_e32 v10, v10, v35
	v_lshlrev_b32_e32 v36, 16, v19
	v_add_f32_e32 v10, v10, v18
	v_and_b32_e32 v19, 0xffff0000, v19
	v_add_f32_e32 v10, v10, v36
	v_lshlrev_b32_e32 v37, 16, v20
	v_add_f32_e32 v10, v10, v19
	v_and_b32_e32 v20, 0xffff0000, v20
	v_add_f32_e32 v10, v10, v37
	v_lshlrev_b32_e32 v38, 16, v21
	v_add_f32_e32 v10, v10, v20
	v_and_b32_e32 v21, 0xffff0000, v21
	v_add_f32_e32 v10, v10, v38
	v_lshlrev_b32_e32 v39, 16, v22
	v_add_f32_e32 v10, v10, v21
	v_and_b32_e32 v22, 0xffff0000, v22
	v_add_f32_e32 v10, v10, v39
	v_lshlrev_b32_e32 v40, 16, v23
	v_add_f32_e32 v10, v10, v22
	v_and_b32_e32 v23, 0xffff0000, v23
	v_add_f32_e32 v10, v10, v40
	v_lshlrev_b32_e32 v41, 16, v24
	v_add_f32_e32 v10, v10, v23
	v_and_b32_e32 v24, 0xffff0000, v24
	v_add_f32_e32 v10, v10, v41
	v_lshlrev_b32_e32 v42, 16, v25
	v_add_f32_e32 v10, v10, v24
	v_and_b32_e32 v25, 0xffff0000, v25
	v_add_f32_e32 v10, v10, v42
	v_add_f32_e32 v10, v10, v25
	s_waitcnt lgkmcnt(0)
	s_nop 1
	v_add_f32_dpp v10, v10, v10 quad_perm:[1,0,3,2] row_mask:0xf bank_mask:0xf
	s_waitcnt lgkmcnt(0)
	s_nop 1
	v_add_f32_dpp v10, v10, v10 quad_perm:[2,3,0,1] row_mask:0xf bank_mask:0xf
	s_waitcnt lgkmcnt(0)
	s_nop 1
	v_add_f32_dpp v10, v10, v10 row_half_mirror row_mask:0xf bank_mask:0xf
	s_waitcnt lgkmcnt(0)
	s_nop 1
	v_add_f32_dpp v10, v10, v10 row_mirror row_mask:0xf bank_mask:0xf
	ds_bpermute_b32 v43, v8, v10
	s_waitcnt lgkmcnt(0)
	v_add_f32_e32 v10, v10, v43
	ds_bpermute_b32 v43, v9, v10
	s_waitcnt lgkmcnt(0)
	v_add_f32_e32 v10, v10, v43
	v_fmac_f32_e32 v27, 0xba000000, v10
	v_fmac_f32_e32 v26, 0xba000000, v10
	v_mul_f32_e32 v27, v27, v27
	v_fmac_f32_e32 v28, 0xba000000, v10
	v_fmac_f32_e32 v27, v26, v26
	v_fmac_f32_e32 v11, 0xba000000, v10
	v_fmac_f32_e32 v27, v28, v28
	v_fmac_f32_e32 v29, 0xba000000, v10
	v_fmac_f32_e32 v27, v11, v11
	v_fmac_f32_e32 v12, 0xba000000, v10
	v_fmac_f32_e32 v27, v29, v29
	v_fmac_f32_e32 v30, 0xba000000, v10
	v_fmac_f32_e32 v27, v12, v12
	v_fmac_f32_e32 v13, 0xba000000, v10
	v_fmac_f32_e32 v27, v30, v30
	v_fmac_f32_e32 v31, 0xba000000, v10
	v_fmac_f32_e32 v27, v13, v13
	v_fmac_f32_e32 v14, 0xba000000, v10
	v_fmac_f32_e32 v27, v31, v31
	v_fmac_f32_e32 v32, 0xba000000, v10
	v_fmac_f32_e32 v27, v14, v14
	v_fmac_f32_e32 v15, 0xba000000, v10
	v_fmac_f32_e32 v27, v32, v32
	v_fmac_f32_e32 v33, 0xba000000, v10
	v_fmac_f32_e32 v27, v15, v15
	v_fmac_f32_e32 v16, 0xba000000, v10
	v_fmac_f32_e32 v27, v33, v33
	v_fmac_f32_e32 v34, 0xba000000, v10
	v_fmac_f32_e32 v27, v16, v16
	v_fmac_f32_e32 v17, 0xba000000, v10
	v_fmac_f32_e32 v27, v34, v34
	v_fmac_f32_e32 v35, 0xba000000, v10
	v_fmac_f32_e32 v27, v17, v17
	v_fmac_f32_e32 v18, 0xba000000, v10
	v_fmac_f32_e32 v27, v35, v35
	v_fmac_f32_e32 v36, 0xba000000, v10
	v_fmac_f32_e32 v27, v18, v18
	v_fmac_f32_e32 v19, 0xba000000, v10
	v_fmac_f32_e32 v27, v36, v36
	v_fmac_f32_e32 v37, 0xba000000, v10
	v_fmac_f32_e32 v27, v19, v19
	v_fmac_f32_e32 v20, 0xba000000, v10
	v_fmac_f32_e32 v27, v37, v37
	v_fmac_f32_e32 v38, 0xba000000, v10
	v_fmac_f32_e32 v27, v20, v20
	v_fmac_f32_e32 v21, 0xba000000, v10
	v_fmac_f32_e32 v27, v38, v38
	v_fmac_f32_e32 v39, 0xba000000, v10
	v_fmac_f32_e32 v27, v21, v21
	v_fmac_f32_e32 v22, 0xba000000, v10
	v_fmac_f32_e32 v27, v39, v39
	v_fmac_f32_e32 v40, 0xba000000, v10
	v_fmac_f32_e32 v27, v22, v22
	v_fmac_f32_e32 v23, 0xba000000, v10
	v_fmac_f32_e32 v27, v40, v40
	v_fmac_f32_e32 v41, 0xba000000, v10
	v_fmac_f32_e32 v27, v23, v23
	v_fmac_f32_e32 v24, 0xba000000, v10
	v_fmac_f32_e32 v27, v41, v41
	v_fmac_f32_e32 v42, 0xba000000, v10
	v_fmac_f32_e32 v27, v24, v24
	v_fmac_f32_e32 v27, v42, v42
	v_fmac_f32_e32 v25, 0xba000000, v10
	v_fmac_f32_e32 v27, v25, v25
	s_waitcnt lgkmcnt(0)
	s_nop 1
	v_add_f32_dpp v11, v27, v27 quad_perm:[1,0,3,2] row_mask:0xf bank_mask:0xf
	s_waitcnt lgkmcnt(0)
	s_nop 1
	v_add_f32_dpp v11, v11, v11 quad_perm:[2,3,0,1] row_mask:0xf bank_mask:0xf
	s_waitcnt lgkmcnt(0)
	s_nop 1
	v_add_f32_dpp v11, v11, v11 row_half_mirror row_mask:0xf bank_mask:0xf
	s_waitcnt lgkmcnt(0)
	s_nop 1
	v_add_f32_dpp v11, v11, v11 row_mirror row_mask:0xf bank_mask:0xf
	ds_bpermute_b32 v12, v8, v11
	s_waitcnt lgkmcnt(0)
	v_add_f32_e32 v11, v11, v12
	ds_bpermute_b32 v12, v9, v11
	s_and_saveexec_b64 s[14:15], vcc
	s_cbranch_execz .LBB0_1088
	s_waitcnt lgkmcnt(0)
	v_add_f32_e32 v11, v11, v12
	v_fmamk_f32 v11, v11, 0x3a000000, v0
	v_mul_f32_e32 v12, 0x4b800000, v11
	v_cmp_gt_f32_e64 s[8:9], s5, v11
	s_ashr_i32 s11, s10, 31
	s_lshl_b64 s[20:21], s[10:11], 2
	v_cndmask_b32_e64 v11, v11, v12, s[8:9]
	v_rsq_f32_e32 v11, v11
	s_add_u32 s20, s16, s20
	v_mul_f32_e32 v10, 0x3a000000, v10
	s_addc_u32 s21, s17, s21
	v_mul_f32_e32 v12, 0x45800000, v11
	v_cndmask_b32_e64 v11, v11, v12, s[8:9]
	global_store_dwordx2 v1, v[10:11], s[20:21]
	s_branch .LBB0_1088
